# v36 plus hand-written grid barrier: the chip's last arriver (returning top arrival) bumps all per-XCC generation words itself; no top-generation word, no relay through the other leaders
# speedup vs baseline: 1.0136x; 1.0136x over previous
.LBB0_95:
	s_getreg_b32 s98, hwreg(HW_REG_XCC_ID, 0, 4)
	s_lshl_b32 s98, s98, 8
	v_mov_b32_e32 v1, 0x21160
	ds_read_b64 v[2:3], v1
	v_mov_b32_e32 v4, s98
	v_add_u32_e32 v4, 0x5400, v4
	v_mov_b32_e32 v5, 1
	global_atomic_add v6, v4, v5, s[54:55] sc0
	v_add_u32_e32 v7, 0x1000, v4
	s_waitcnt lgkmcnt(0)
	v_mul_u32_u24_e32 v2, 1, v2
	v_mul_u32_u24_e32 v3, 1, v3
	s_waitcnt vmcnt(0)
	v_add_u32_e32 v6, 1, v6
	v_cmp_ne_u32_e32 vcc, v6, v2
	s_cbranch_vccnz .Lgb4_1_follow
	buffer_wbl2 sc1
	s_waitcnt vmcnt(0)
	v_mov_b32_e32 v4, 0x7400
	global_atomic_add v6, v4, v5, s[54:55] sc0
	s_waitcnt vmcnt(0)
	v_add_u32_e32 v6, 1, v6
	v_cmp_ne_u32_e32 vcc, v6, v3
	s_cbranch_vccnz .Lgb4_1_follow
	v_mov_b32_e32 v4, 0x6400
	global_atomic_add v4, v5, s[54:55]
	global_atomic_add v4, v5, s[54:55] offset:256
	global_atomic_add v4, v5, s[54:55] offset:512
	global_atomic_add v4, v5, s[54:55] offset:768
	global_atomic_add v4, v5, s[54:55] offset:1024
	global_atomic_add v4, v5, s[54:55] offset:1280
	global_atomic_add v4, v5, s[54:55] offset:1536
	global_atomic_add v4, v5, s[54:55] offset:1792
	global_atomic_add v4, v5, s[54:55] offset:2048
	global_atomic_add v4, v5, s[54:55] offset:2304
	global_atomic_add v4, v5, s[54:55] offset:2560
	global_atomic_add v4, v5, s[54:55] offset:2816
	global_atomic_add v4, v5, s[54:55] offset:3072
	global_atomic_add v4, v5, s[54:55] offset:3328
	global_atomic_add v4, v5, s[54:55] offset:3584
	global_atomic_add v4, v5, s[54:55] offset:3840
	s_branch .Lgb4_1_acq
.Lgb4_1_follow:
	v_mov_b32_e32 v2, 1
	s_mov_b32 s99, 0
.Lgb4_1_gen:
	global_load_dword v6, v7, s[54:55] sc1
	s_waitcnt vmcnt(0)
	v_cmp_ge_u32_e32 vcc, v6, v2
	s_cbranch_vccnz .Lgb4_1_acq
	s_add_i32 s99, s99, 1
	s_cmp_gt_u32 s99, 0x40000
	s_cbranch_scc1 .Lgb4_1_acq
	s_sleep 1
	s_branch .Lgb4_1_gen

.LBB0_236:
	s_getreg_b32 s98, hwreg(HW_REG_XCC_ID, 0, 4)
	s_lshl_b32 s98, s98, 8
	v_mov_b32_e32 v1, 0x21160
	ds_read_b64 v[2:3], v1
	v_mov_b32_e32 v4, s98
	v_add_u32_e32 v4, 0x5400, v4
	v_mov_b32_e32 v5, 1
	global_atomic_add v6, v4, v5, s[54:55] sc0
	v_add_u32_e32 v7, 0x1000, v4
	s_waitcnt lgkmcnt(0)
	v_mul_u32_u24_e32 v2, 2, v2
	v_mul_u32_u24_e32 v3, 2, v3
	s_waitcnt vmcnt(0)
	v_add_u32_e32 v6, 1, v6
	v_cmp_ne_u32_e32 vcc, v6, v2
	s_cbranch_vccnz .Lgb4_2_follow
	buffer_wbl2 sc1
	s_waitcnt vmcnt(0)
	v_mov_b32_e32 v4, 0x7400
	global_atomic_add v6, v4, v5, s[54:55] sc0
	s_waitcnt vmcnt(0)
	v_add_u32_e32 v6, 1, v6
	v_cmp_ne_u32_e32 vcc, v6, v3
	s_cbranch_vccnz .Lgb4_2_follow
	v_mov_b32_e32 v4, 0x6400
	global_atomic_add v4, v5, s[54:55]
	global_atomic_add v4, v5, s[54:55] offset:256
	global_atomic_add v4, v5, s[54:55] offset:512
	global_atomic_add v4, v5, s[54:55] offset:768
	global_atomic_add v4, v5, s[54:55] offset:1024
	global_atomic_add v4, v5, s[54:55] offset:1280
	global_atomic_add v4, v5, s[54:55] offset:1536
	global_atomic_add v4, v5, s[54:55] offset:1792
	global_atomic_add v4, v5, s[54:55] offset:2048
	global_atomic_add v4, v5, s[54:55] offset:2304
	global_atomic_add v4, v5, s[54:55] offset:2560
	global_atomic_add v4, v5, s[54:55] offset:2816
	global_atomic_add v4, v5, s[54:55] offset:3072
	global_atomic_add v4, v5, s[54:55] offset:3328
	global_atomic_add v4, v5, s[54:55] offset:3584
	global_atomic_add v4, v5, s[54:55] offset:3840
	s_branch .Lgb4_2_acq
.Lgb4_2_follow:
	v_mov_b32_e32 v2, 2
	s_mov_b32 s99, 0

.LBB0_324:
	s_getreg_b32 s98, hwreg(HW_REG_XCC_ID, 0, 4)
	s_lshl_b32 s98, s98, 8
	v_mov_b32_e32 v1, 0x21160
	ds_read_b64 v[2:3], v1
	v_mov_b32_e32 v4, s98
	v_add_u32_e32 v4, 0x5400, v4
	v_mov_b32_e32 v5, 1
	global_atomic_add v6, v4, v5, s[54:55] sc0
	v_add_u32_e32 v7, 0x1000, v4
	s_waitcnt lgkmcnt(0)
	v_mul_u32_u24_e32 v2, 3, v2
	v_mul_u32_u24_e32 v3, 3, v3
	s_waitcnt vmcnt(0)
	v_add_u32_e32 v6, 1, v6
	v_cmp_ne_u32_e32 vcc, v6, v2
	s_cbranch_vccnz .Lgb4_3_follow
	buffer_wbl2 sc1
	s_waitcnt vmcnt(0)
	v_mov_b32_e32 v4, 0x7400
	global_atomic_add v6, v4, v5, s[54:55] sc0
	s_waitcnt vmcnt(0)
	v_add_u32_e32 v6, 1, v6
	v_cmp_ne_u32_e32 vcc, v6, v3
	s_cbranch_vccnz .Lgb4_3_follow
	v_mov_b32_e32 v4, 0x6400
	global_atomic_add v4, v5, s[54:55]
	global_atomic_add v4, v5, s[54:55] offset:256
	global_atomic_add v4, v5, s[54:55] offset:512
	global_atomic_add v4, v5, s[54:55] offset:768
	global_atomic_add v4, v5, s[54:55] offset:1024
	global_atomic_add v4, v5, s[54:55] offset:1280
	global_atomic_add v4, v5, s[54:55] offset:1536
	global_atomic_add v4, v5, s[54:55] offset:1792
	global_atomic_add v4, v5, s[54:55] offset:2048
	global_atomic_add v4, v5, s[54:55] offset:2304
	global_atomic_add v4, v5, s[54:55] offset:2560
	global_atomic_add v4, v5, s[54:55] offset:2816
	global_atomic_add v4, v5, s[54:55] offset:3072
	global_atomic_add v4, v5, s[54:55] offset:3328
	global_atomic_add v4, v5, s[54:55] offset:3584
	global_atomic_add v4, v5, s[54:55] offset:3840
	s_branch .Lgb4_3_acq
.Lgb4_3_follow:
	v_mov_b32_e32 v2, 3
	s_mov_b32 s99, 0

.LBB0_406:
	s_getreg_b32 s98, hwreg(HW_REG_XCC_ID, 0, 4)
	s_lshl_b32 s98, s98, 8
	v_mov_b32_e32 v1, 0x21160
	ds_read_b64 v[2:3], v1
	v_mov_b32_e32 v4, s98
	v_add_u32_e32 v4, 0x5400, v4
	v_mov_b32_e32 v5, 1
	global_atomic_add v6, v4, v5, s[54:55] sc0
	v_add_u32_e32 v7, 0x1000, v4
	s_waitcnt lgkmcnt(0)
	v_mul_u32_u24_e32 v2, 4, v2
	v_mul_u32_u24_e32 v3, 4, v3
	s_waitcnt vmcnt(0)
	v_add_u32_e32 v6, 1, v6
	v_cmp_ne_u32_e32 vcc, v6, v2
	s_cbranch_vccnz .Lgb4_4_follow
	buffer_wbl2 sc1
	s_waitcnt vmcnt(0)
	v_mov_b32_e32 v4, 0x7400
	global_atomic_add v6, v4, v5, s[54:55] sc0
	s_waitcnt vmcnt(0)
	v_add_u32_e32 v6, 1, v6
	v_cmp_ne_u32_e32 vcc, v6, v3
	s_cbranch_vccnz .Lgb4_4_follow
	v_mov_b32_e32 v4, 0x6400
	global_atomic_add v4, v5, s[54:55]
	global_atomic_add v4, v5, s[54:55] offset:256
	global_atomic_add v4, v5, s[54:55] offset:512
	global_atomic_add v4, v5, s[54:55] offset:768
	global_atomic_add v4, v5, s[54:55] offset:1024
	global_atomic_add v4, v5, s[54:55] offset:1280
	global_atomic_add v4, v5, s[54:55] offset:1536
	global_atomic_add v4, v5, s[54:55] offset:1792
	global_atomic_add v4, v5, s[54:55] offset:2048
	global_atomic_add v4, v5, s[54:55] offset:2304
	global_atomic_add v4, v5, s[54:55] offset:2560
	global_atomic_add v4, v5, s[54:55] offset:2816
	global_atomic_add v4, v5, s[54:55] offset:3072
	global_atomic_add v4, v5, s[54:55] offset:3328
	global_atomic_add v4, v5, s[54:55] offset:3584
	global_atomic_add v4, v5, s[54:55] offset:3840
	s_branch .Lgb4_4_acq
.Lgb4_4_follow:
	v_mov_b32_e32 v2, 4
	s_mov_b32 s99, 0

.LBB0_536:
	s_getreg_b32 s98, hwreg(HW_REG_XCC_ID, 0, 4)
	s_lshl_b32 s98, s98, 8
	v_mov_b32_e32 v1, 0x21160
	ds_read_b64 v[2:3], v1
	v_mov_b32_e32 v4, s98
	v_add_u32_e32 v4, 0x5400, v4
	v_mov_b32_e32 v5, 1
	global_atomic_add v6, v4, v5, s[54:55] sc0
	v_add_u32_e32 v7, 0x1000, v4
	s_waitcnt lgkmcnt(0)
	v_mul_u32_u24_e32 v2, 5, v2
	v_mul_u32_u24_e32 v3, 5, v3
	s_waitcnt vmcnt(0)
	v_add_u32_e32 v6, 1, v6
	v_cmp_ne_u32_e32 vcc, v6, v2
	s_cbranch_vccnz .Lgb4_5_follow
	buffer_wbl2 sc1
	s_waitcnt vmcnt(0)
	v_mov_b32_e32 v4, 0x7400
	global_atomic_add v6, v4, v5, s[54:55] sc0
	s_waitcnt vmcnt(0)
	v_add_u32_e32 v6, 1, v6
	v_cmp_ne_u32_e32 vcc, v6, v3
	s_cbranch_vccnz .Lgb4_5_follow
	v_mov_b32_e32 v4, 0x6400
	global_atomic_add v4, v5, s[54:55]
	global_atomic_add v4, v5, s[54:55] offset:256
	global_atomic_add v4, v5, s[54:55] offset:512
	global_atomic_add v4, v5, s[54:55] offset:768
	global_atomic_add v4, v5, s[54:55] offset:1024
	global_atomic_add v4, v5, s[54:55] offset:1280
	global_atomic_add v4, v5, s[54:55] offset:1536
	global_atomic_add v4, v5, s[54:55] offset:1792
	global_atomic_add v4, v5, s[54:55] offset:2048
	global_atomic_add v4, v5, s[54:55] offset:2304
	global_atomic_add v4, v5, s[54:55] offset:2560
	global_atomic_add v4, v5, s[54:55] offset:2816
	global_atomic_add v4, v5, s[54:55] offset:3072
	global_atomic_add v4, v5, s[54:55] offset:3328
	global_atomic_add v4, v5, s[54:55] offset:3584
	global_atomic_add v4, v5, s[54:55] offset:3840
	s_branch .Lgb4_5_acq
.Lgb4_5_follow:
	v_mov_b32_e32 v2, 5
	s_mov_b32 s99, 0

.LBB0_604:
	s_getreg_b32 s98, hwreg(HW_REG_XCC_ID, 0, 4)
	s_lshl_b32 s98, s98, 8
	v_mov_b32_e32 v1, 0x21160
	ds_read_b64 v[2:3], v1
	v_mov_b32_e32 v4, s98
	v_add_u32_e32 v4, 0x5400, v4
	v_mov_b32_e32 v5, 1
	global_atomic_add v6, v4, v5, s[54:55] sc0
	v_add_u32_e32 v7, 0x1000, v4
	s_waitcnt lgkmcnt(0)
	v_mul_u32_u24_e32 v2, 6, v2
	v_mul_u32_u24_e32 v3, 6, v3
	s_waitcnt vmcnt(0)
	v_add_u32_e32 v6, 1, v6
	v_cmp_ne_u32_e32 vcc, v6, v2
	s_cbranch_vccnz .Lgb4_6_follow
	buffer_wbl2 sc1
	s_waitcnt vmcnt(0)
	v_mov_b32_e32 v4, 0x7400
	global_atomic_add v6, v4, v5, s[54:55] sc0
	s_waitcnt vmcnt(0)
	v_add_u32_e32 v6, 1, v6
	v_cmp_ne_u32_e32 vcc, v6, v3
	s_cbranch_vccnz .Lgb4_6_follow
	v_mov_b32_e32 v4, 0x6400
	global_atomic_add v4, v5, s[54:55]
	global_atomic_add v4, v5, s[54:55] offset:256
	global_atomic_add v4, v5, s[54:55] offset:512
	global_atomic_add v4, v5, s[54:55] offset:768
	global_atomic_add v4, v5, s[54:55] offset:1024
	global_atomic_add v4, v5, s[54:55] offset:1280
	global_atomic_add v4, v5, s[54:55] offset:1536
	global_atomic_add v4, v5, s[54:55] offset:1792
	global_atomic_add v4, v5, s[54:55] offset:2048
	global_atomic_add v4, v5, s[54:55] offset:2304
	global_atomic_add v4, v5, s[54:55] offset:2560
	global_atomic_add v4, v5, s[54:55] offset:2816
	global_atomic_add v4, v5, s[54:55] offset:3072
	global_atomic_add v4, v5, s[54:55] offset:3328
	global_atomic_add v4, v5, s[54:55] offset:3584
	global_atomic_add v4, v5, s[54:55] offset:3840
	s_branch .Lgb4_6_acq
.Lgb4_6_follow:
	v_mov_b32_e32 v2, 6
	s_mov_b32 s99, 0
